# P3c/P5 scaled fp8 conversion + redundant zero-inits of cvt destinations removed (P3c, P5)
# baseline (speedup 1.0000x reference)
;   __device__ __forceinline__ void operator()(const Acc& acc, const GUnit& u, int wr, int wc, int fr, int fq) const {
;     const int row0 = u.pm * 256 + wr * 64 + fr;
;     unsigned char* ob = Q0 + (size_t)u.pn * 256 + wc * 32 + 8 * fq;
; #pragma unroll
;     for (int ai = 0; ai < 2; ++ai)
; #pragma unroll
;       for (int m = 0; m < 4; ++m) {
;         const int row = row0 + ai * 128 + m * 16;
; #pragma unroll
;         for (int bj = 0; bj < 2; ++bj) { const f32x4 a = acc[ai][bj][m][0] * osc, b = acc[ai][bj][m][1] * osc; u32x2 w;
;           w[0] = __builtin_amdgcn_cvt_pk_fp8_f32(a[0], a[1], 0, false); w[0] = __builtin_amdgcn_cvt_pk_fp8_f32(a[2], a[3], w[0], true);
;           w[1] = __builtin_amdgcn_cvt_pk_fp8_f32(b[0], b[1], 0, false); w[1] = __builtin_amdgcn_cvt_pk_fp8_f32(b[2], b[3], w[1], true);
;           *(u32x2*)(ob + (size_t)row * 8192 + bj * 128) = w; }
;       }
;   }
.LBB0_972:
	v_mov_b32_e32 v0, v200
	s_lshl_b32 s8, s30, 8
	v_readfirstlane_b32 s27, v0
	s_ashr_i32 s9, s27, 2
	s_andn2_b32 s9, s9, 63
	s_add_i32 s9, s9, s8
	v_and_or_b32 v2, v0, 15, s9
	v_lshrrev_b32_e32 v0, 1, v0
	v_and_b32_e32 v64, 24, v0
	v_and_b32_e32 v210, 8, v200
	v_mov_b32_e32 v212, 0x10000
	v_lshl_or_b32 v64, v210, 2, v64
	v_xor_b32_e32 v210, 8, v210
	v_mov_b32_e32 v213, 0
	v_lshl_or_b32 v64, v210, 13, v64
	v_cvt_scalef32_pk_fp8_f32 v8, v192, v193, s14
	v_cvt_scalef32_pk_fp8_f32 v9, v188, v189, s14
	s_ashr_i32 s35, s34, 31
	s_lshl_b64 s[8:9], s[34:35], 8
	v_cvt_scalef32_pk_fp8_f32 v8, v194, v195, s14 op_sel:[0,0,0,1]
	v_cvt_scalef32_pk_fp8_f32 v9, v190, v191, s14 op_sel:[0,0,0,1]
	s_add_u32 s8, s92, s8
	v_cvt_scalef32_pk_fp8_f32 v10, v184, v185, s14
	v_cvt_scalef32_pk_fp8_f32 v11, v180, v181, s14
	s_addc_u32 s9, s93, s9
	s_and_b32 s27, s27, 0xc0
	s_add_u32 s8, s8, s27
	s_addc_u32 s9, s9, 0
	s_sub_u32 s8, s8, 0x10000
	s_subb_u32 s9, s9, 0
	v_ashrrev_i32_e32 v3, 31, v2
	v_cvt_scalef32_pk_fp8_f32 v10, v186, v187, s14 op_sel:[0,0,0,1]
	v_cvt_scalef32_pk_fp8_f32 v11, v182, v183, s14 op_sel:[0,0,0,1]
	v_lshl_add_u64 v[4:5], s[8:9], 0, v[64:65]
	v_lshlrev_b64 v[0:1], 13, v[2:3]
	v_lshl_add_u64 v[0:1], v[4:5], 0, v[0:1]
	v_mov_b32_e32 v214, v8
	v_mov_b32_e32 v215, v9
	v_mov_b32_dpp v8, v10 row_ror:8 row_mask:0xf bank_mask:0xc
	v_mov_b32_dpp v9, v11 row_ror:8 row_mask:0xf bank_mask:0xc
	v_mov_b32_dpp v10, v214 row_ror:8 row_mask:0xf bank_mask:0x3
	v_mov_b32_dpp v11, v215 row_ror:8 row_mask:0xf bank_mask:0x3
	v_lshl_add_u64 v[216:217], v[0:1], 0, v[212:213]
	global_store_dwordx2 v[0:1], v[8:9], off
	global_store_dwordx2 v[216:217], v[10:11], off
	v_cvt_scalef32_pk_fp8_f32 v12, v160, v161, s14
	v_cvt_scalef32_pk_fp8_f32 v13, v156, v157, s14
	v_cvt_scalef32_pk_fp8_f32 v12, v162, v163, s14 op_sel:[0,0,0,1]
	v_cvt_scalef32_pk_fp8_f32 v13, v158, v159, s14 op_sel:[0,0,0,1]
	v_cvt_scalef32_pk_fp8_f32 v14, v152, v153, s14
	v_cvt_scalef32_pk_fp8_f32 v15, v148, v149, s14
	v_or_b32_e32 v6, 16, v2
	v_ashrrev_i32_e32 v7, 31, v6
	v_cvt_scalef32_pk_fp8_f32 v14, v154, v155, s14 op_sel:[0,0,0,1]
	v_cvt_scalef32_pk_fp8_f32 v15, v150, v151, s14 op_sel:[0,0,0,1]
	v_lshlrev_b64 v[6:7], 13, v[6:7]
	v_lshl_add_u64 v[6:7], v[4:5], 0, v[6:7]
	v_mov_b32_e32 v214, v12
	v_mov_b32_e32 v215, v13
	v_mov_b32_dpp v12, v14 row_ror:8 row_mask:0xf bank_mask:0xc
	v_mov_b32_dpp v13, v15 row_ror:8 row_mask:0xf bank_mask:0xc
	v_mov_b32_dpp v14, v214 row_ror:8 row_mask:0xf bank_mask:0x3
	v_mov_b32_dpp v15, v215 row_ror:8 row_mask:0xf bank_mask:0x3
	v_lshl_add_u64 v[216:217], v[6:7], 0, v[212:213]
	global_store_dwordx2 v[6:7], v[12:13], off
	global_store_dwordx2 v[216:217], v[14:15], off
	v_cvt_scalef32_pk_fp8_f32 v12, v128, v129, s14
	v_cvt_scalef32_pk_fp8_f32 v13, v124, v125, s14
	v_cvt_scalef32_pk_fp8_f32 v12, v130, v131, s14 op_sel:[0,0,0,1]
	v_cvt_scalef32_pk_fp8_f32 v13, v126, v127, s14 op_sel:[0,0,0,1]
	v_cvt_scalef32_pk_fp8_f32 v14, v120, v121, s14
	v_cvt_scalef32_pk_fp8_f32 v15, v116, v117, s14
	v_or_b32_e32 v6, 32, v2
	v_ashrrev_i32_e32 v7, 31, v6
	v_cvt_scalef32_pk_fp8_f32 v14, v122, v123, s14 op_sel:[0,0,0,1]
	v_cvt_scalef32_pk_fp8_f32 v15, v118, v119, s14 op_sel:[0,0,0,1]
	v_lshlrev_b64 v[6:7], 13, v[6:7]
	v_lshl_add_u64 v[6:7], v[4:5], 0, v[6:7]
	v_mov_b32_e32 v214, v12
	v_mov_b32_e32 v215, v13
	v_mov_b32_dpp v12, v14 row_ror:8 row_mask:0xf bank_mask:0xc
	v_mov_b32_dpp v13, v15 row_ror:8 row_mask:0xf bank_mask:0xc
	v_mov_b32_dpp v14, v214 row_ror:8 row_mask:0xf bank_mask:0x3
	v_mov_b32_dpp v15, v215 row_ror:8 row_mask:0xf bank_mask:0x3
	v_lshl_add_u64 v[216:217], v[6:7], 0, v[212:213]
	global_store_dwordx2 v[6:7], v[12:13], off
	global_store_dwordx2 v[216:217], v[14:15], off
	v_cvt_scalef32_pk_fp8_f32 v10, v96, v97, s14
	v_cvt_scalef32_pk_fp8_f32 v11, v92, v93, s14
	v_cvt_scalef32_pk_fp8_f32 v10, v98, v99, s14 op_sel:[0,0,0,1]
	v_cvt_scalef32_pk_fp8_f32 v11, v94, v95, s14 op_sel:[0,0,0,1]
	v_cvt_scalef32_pk_fp8_f32 v12, v88, v89, s14
	v_cvt_scalef32_pk_fp8_f32 v13, v84, v85, s14
	v_or_b32_e32 v2, 48, v2
	v_ashrrev_i32_e32 v3, 31, v2
	v_lshlrev_b64 v[2:3], 13, v[2:3]
	v_cvt_scalef32_pk_fp8_f32 v12, v90, v91, s14 op_sel:[0,0,0,1]
	v_cvt_scalef32_pk_fp8_f32 v13, v86, v87, s14 op_sel:[0,0,0,1]
	v_lshl_add_u64 v[2:3], v[4:5], 0, v[2:3]
	v_cvt_scalef32_pk_fp8_f32 v8, v176, v177, s14
	v_cvt_scalef32_pk_fp8_f32 v9, v172, v173, s14
	v_mov_b32_e32 v214, v10
	v_mov_b32_e32 v215, v11
;   __device__ __forceinline__ void operator()(const Acc& acc, const GUnit& u, int wr, int wc, int fr, int fq) const {
;     const int row0 = u.pm * 256 + wr * 64 + fr;
;     unsigned char* ob = Q0 + (size_t)u.pn * 256 + wc * 32 + 8 * fq;
; #pragma unroll
;     for (int ai = 0; ai < 2; ++ai)
; #pragma unroll
;       for (int m = 0; m < 4; ++m) {
;         const int row = row0 + ai * 128 + m * 16;
; #pragma unroll
;         for (int bj = 0; bj < 2; ++bj) { const f32x4 a = acc[ai][bj][m][0] * osc, b = acc[ai][bj][m][1] * osc; u32x2 w;
;           w[0] = __builtin_amdgcn_cvt_pk_fp8_f32(a[0], a[1], 0, false); w[0] = __builtin_amdgcn_cvt_pk_fp8_f32(a[2], a[3], w[0], true);
;           w[1] = __builtin_amdgcn_cvt_pk_fp8_f32(b[0], b[1], 0, false); w[1] = __builtin_amdgcn_cvt_pk_fp8_f32(b[2], b[3], w[1], true);
;           *(u32x2*)(ob + (size_t)row * 8192 + bj * 128) = w; }
;       }
;   }
	v_mov_b32_dpp v10, v12 row_ror:8 row_mask:0xf bank_mask:0xc
	v_mov_b32_dpp v11, v13 row_ror:8 row_mask:0xf bank_mask:0xc
	v_mov_b32_dpp v12, v214 row_ror:8 row_mask:0xf bank_mask:0x3
	v_mov_b32_dpp v13, v215 row_ror:8 row_mask:0xf bank_mask:0x3
	v_lshl_add_u64 v[216:217], v[2:3], 0, v[212:213]
	global_store_dwordx2 v[2:3], v[10:11], off
	global_store_dwordx2 v[216:217], v[12:13], off
	v_cvt_scalef32_pk_fp8_f32 v8, v178, v179, s14 op_sel:[0,0,0,1]
	v_cvt_scalef32_pk_fp8_f32 v9, v174, v175, s14 op_sel:[0,0,0,1]
	v_cvt_scalef32_pk_fp8_f32 v10, v168, v169, s14
	v_cvt_scalef32_pk_fp8_f32 v11, v164, v165, s14
	v_cvt_scalef32_pk_fp8_f32 v10, v170, v171, s14 op_sel:[0,0,0,1]
	v_cvt_scalef32_pk_fp8_f32 v11, v166, v167, s14 op_sel:[0,0,0,1]
	v_add_co_u32_e32 v4, vcc, s54, v0
	v_lshl_add_u64 v[2:3], v[0:1], 0, s[16:17]
	s_nop 0
	v_addc_co_u32_e32 v5, vcc, 0, v1, vcc
	v_mov_b32_e32 v214, v8
	v_mov_b32_e32 v215, v9
	v_mov_b32_dpp v8, v10 row_ror:8 row_mask:0xf bank_mask:0xc
	v_mov_b32_dpp v9, v11 row_ror:8 row_mask:0xf bank_mask:0xc
	v_mov_b32_dpp v10, v214 row_ror:8 row_mask:0xf bank_mask:0x3
	v_mov_b32_dpp v11, v215 row_ror:8 row_mask:0xf bank_mask:0x3
	v_lshl_add_u64 v[216:217], v[4:5], 0, v[212:213]
	global_store_dwordx2 v[4:5], v[8:9], off
	global_store_dwordx2 v[216:217], v[10:11], off
	v_cvt_scalef32_pk_fp8_f32 v8, v144, v145, s14
	v_cvt_scalef32_pk_fp8_f32 v9, v140, v141, s14
	v_cvt_scalef32_pk_fp8_f32 v8, v146, v147, s14 op_sel:[0,0,0,1]
	v_cvt_scalef32_pk_fp8_f32 v9, v142, v143, s14 op_sel:[0,0,0,1]
	v_cvt_scalef32_pk_fp8_f32 v10, v136, v137, s14
	v_cvt_scalef32_pk_fp8_f32 v11, v132, v133, s14
	v_cvt_scalef32_pk_fp8_f32 v10, v138, v139, s14 op_sel:[0,0,0,1]
	v_cvt_scalef32_pk_fp8_f32 v11, v134, v135, s14 op_sel:[0,0,0,1]
	v_add_co_u32_e32 v4, vcc, s55, v0
	v_lshl_add_u64 v[2:3], v[0:1], 0, s[18:19]
	s_nop 0
	v_addc_co_u32_e32 v5, vcc, 0, v1, vcc
	v_mov_b32_e32 v214, v8
	v_mov_b32_e32 v215, v9
	v_mov_b32_dpp v8, v10 row_ror:8 row_mask:0xf bank_mask:0xc
	v_mov_b32_dpp v9, v11 row_ror:8 row_mask:0xf bank_mask:0xc
	v_mov_b32_dpp v10, v214 row_ror:8 row_mask:0xf bank_mask:0x3
	v_mov_b32_dpp v11, v215 row_ror:8 row_mask:0xf bank_mask:0x3
	v_lshl_add_u64 v[216:217], v[4:5], 0, v[212:213]
	global_store_dwordx2 v[4:5], v[8:9], off
	global_store_dwordx2 v[216:217], v[10:11], off
	v_cvt_scalef32_pk_fp8_f32 v8, v112, v113, s14
	v_cvt_scalef32_pk_fp8_f32 v9, v108, v109, s14
	v_cvt_scalef32_pk_fp8_f32 v8, v114, v115, s14 op_sel:[0,0,0,1]
	v_cvt_scalef32_pk_fp8_f32 v9, v110, v111, s14 op_sel:[0,0,0,1]
	v_cvt_scalef32_pk_fp8_f32 v10, v104, v105, s14
	v_cvt_scalef32_pk_fp8_f32 v11, v100, v101, s14
	v_cvt_scalef32_pk_fp8_f32 v10, v106, v107, s14 op_sel:[0,0,0,1]
	v_cvt_scalef32_pk_fp8_f32 v11, v102, v103, s14 op_sel:[0,0,0,1]
	v_add_co_u32_e32 v4, vcc, s56, v0
	v_lshl_add_u64 v[2:3], v[0:1], 0, s[20:21]
	s_nop 0
	v_addc_co_u32_e32 v5, vcc, 0, v1, vcc
	v_mov_b32_e32 v214, v8
	v_mov_b32_e32 v215, v9
	v_mov_b32_dpp v8, v10 row_ror:8 row_mask:0xf bank_mask:0xc
	v_mov_b32_dpp v9, v11 row_ror:8 row_mask:0xf bank_mask:0xc
	v_mov_b32_dpp v10, v214 row_ror:8 row_mask:0xf bank_mask:0x3
	v_mov_b32_dpp v11, v215 row_ror:8 row_mask:0xf bank_mask:0x3
	v_lshl_add_u64 v[216:217], v[4:5], 0, v[212:213]
	global_store_dwordx2 v[4:5], v[8:9], off
	global_store_dwordx2 v[216:217], v[10:11], off
	v_cvt_scalef32_pk_fp8_f32 v8, v80, v81, s14
	v_cvt_scalef32_pk_fp8_f32 v9, v76, v77, s14
	v_cvt_scalef32_pk_fp8_f32 v8, v82, v83, s14 op_sel:[0,0,0,1]
	v_cvt_scalef32_pk_fp8_f32 v9, v78, v79, s14 op_sel:[0,0,0,1]
	v_cvt_scalef32_pk_fp8_f32 v10, v72, v73, s14
	v_cvt_scalef32_pk_fp8_f32 v11, v68, v69, s14
	v_lshl_add_u64 v[2:3], v[0:1], 0, s[22:23]
	v_cvt_scalef32_pk_fp8_f32 v10, v74, v75, s14 op_sel:[0,0,0,1]
	v_cvt_scalef32_pk_fp8_f32 v11, v70, v71, s14 op_sel:[0,0,0,1]
	v_add_co_u32_e32 v0, vcc, s57, v0
	s_mov_b64 s[8:9], -1
	s_nop 0
	v_addc_co_u32_e32 v1, vcc, 0, v1, vcc
	s_andn2_b64 vcc, exec, s[24:25]
	v_mov_b32_e32 v214, v8
	v_mov_b32_e32 v215, v9
	v_mov_b32_dpp v8, v10 row_ror:8 row_mask:0xf bank_mask:0xc
	v_mov_b32_dpp v9, v11 row_ror:8 row_mask:0xf bank_mask:0xc
	v_mov_b32_dpp v10, v214 row_ror:8 row_mask:0xf bank_mask:0x3
	v_mov_b32_dpp v11, v215 row_ror:8 row_mask:0xf bank_mask:0x3
	v_lshl_add_u64 v[216:217], v[0:1], 0, v[212:213]
	global_store_dwordx2 v[0:1], v[8:9], off
	global_store_dwordx2 v[216:217], v[10:11], off
	s_cbranch_vccnz .LBB0_954
	s_andn2_b64 vcc, exec, s[10:11]
	s_cbranch_vccnz .LBB0_953
	s_barrier
	s_branch .LBB0_953

; __device__ __forceinline__ float silu_fast(float z) { return z * __builtin_amdgcn_rcpf(1.f + __builtin_amdgcn_exp2f(-1.4426950408889634f * z)); }
;   __device__ __forceinline__ void operator()(const Acc& acc, const GUnit& u, int wr, int wc, int fr, int fq) const {
;     const int row0 = u.pm * 256 + wr * 64 + fr; const int col0 = u.pn * 256 + wc * 32 + 8 * fq;
; #pragma unroll
;     for (int ai = 0; ai < 2; ++ai)
; #pragma unroll
;       for (int m = 0; m < 4; ++m) {
;         const size_t off = (size_t)(row0 + ai * 128 + m * 16) * 4096 + col0;
; #pragma unroll
;         for (int bj = 0; bj < 2; ++bj) {
;           const u32x2 zw = *(const u32x2*)(Z + off + bj * 128);
;           typedef float f32x2v __attribute__((ext_vector_type(2)));
;           const f32x2v z0 = __builtin_amdgcn_cvt_pk_f32_fp8(zw[0], false), z1 = __builtin_amdgcn_cvt_pk_f32_fp8(zw[0], true), z2 = __builtin_amdgcn_cvt_pk_f32_fp8(zw[1], false), z3 = __builtin_amdgcn_cvt_pk_f32_fp8(zw[1], true);
;           f32x4 a = acc[ai][bj][m][0] * osc, b = acc[ai][bj][m][1] * osc;
;           a[0] *= silu_fast(z0[0]); a[1] *= silu_fast(z0[1]); a[2] *= silu_fast(z1[0]); a[3] *= silu_fast(z1[1]);
;           b[0] *= silu_fast(z2[0]); b[1] *= silu_fast(z2[1]); b[2] *= silu_fast(z3[0]); b[3] *= silu_fast(z3[1]);
;           u32x2 w; w[0] = __builtin_amdgcn_cvt_pk_fp8_f32(a[0], a[1], 0, false); w[0] = __builtin_amdgcn_cvt_pk_fp8_f32(a[2], a[3], w[0], true);
;           w[1] = __builtin_amdgcn_cvt_pk_fp8_f32(b[0], b[1], 0, false); w[1] = __builtin_amdgcn_cvt_pk_fp8_f32(b[2], b[3], w[1], true);
;           *(u32x2*)(Y + off + bj * 128) = w;
;         }
.LBB0_1047:
	v_mov_b32_e32 v132, v200
	s_lshl_b32 s28, s28, 8
	v_readfirstlane_b32 s23, v132
	s_ashr_i32 s30, s23, 2
	s_andn2_b32 s30, s30, 63
	s_lshr_b32 s23, s23, 1
	s_add_i32 s30, s30, s28
	s_lshl_b32 s28, s46, 8
	s_and_b32 s23, s23, 0x60
	v_and_or_b32 v134, v132, 15, s30
	s_or_b32 s23, s23, s28
	v_lshrrev_b32_e32 v132, 1, v132
	v_and_or_b32 v136, v132, 24, s23
	v_ashrrev_i32_e32 v135, 31, v134
	v_ashrrev_i32_e32 v137, 31, v136
	v_lshlrev_b64 v[132:133], 12, v[134:135]
	v_readlane_b32 s30, v254, 38
	v_lshl_add_u64 v[132:133], v[132:133], 0, v[136:137]
	v_readlane_b32 s31, v254, 39
	v_mov_b32_e32 v147, 0
	v_lshl_add_u64 v[142:143], s[30:31], 0, v[132:133]
	global_load_dwordx2 v[144:145], v[142:143], off
	s_nop 0
	global_load_dwordx2 v[142:143], v[142:143], off offset:128
	v_mov_b32_e32 v146, 0
	v_readlane_b32 s36, v254, 16
	v_readlane_b32 s38, v254, 18
	v_readlane_b32 s39, v254, 19
	s_andn2_b64 vcc, exec, s[20:21]
	s_mov_b64 s[20:21], -1
	v_readlane_b32 s37, v254, 17
	s_waitcnt vmcnt(0)
	v_cvt_pk_f32_fp8_e32 v[148:149], v144
	v_cvt_pk_f32_fp8_sdwa v[150:151], v144 src0_sel:WORD_1
	v_cvt_pk_f32_fp8_e32 v[152:153], v145
	v_cvt_pk_f32_fp8_sdwa v[144:145], v145 src0_sel:WORD_1
	v_mul_f32_e32 v135, 0xbfb8aa3b, v148
	v_mul_f32_e32 v160, 0xbfb8aa3b, v149
	v_mul_f32_e32 v161, 0xbfb8aa3b, v150
	v_mul_f32_e32 v162, 0xbfb8aa3b, v151
	v_mul_f32_e32 v163, 0xbfb8aa3b, v152
	v_mul_f32_e32 v164, 0xbfb8aa3b, v153
	v_exp_f32_e32 v135, v135
	v_exp_f32_e32 v160, v160
	v_exp_f32_e32 v161, v161
	v_exp_f32_e32 v162, v162
	v_exp_f32_e32 v163, v163
	v_exp_f32_e32 v164, v164
	v_mul_f32_e32 v165, 0xbfb8aa3b, v144
	v_mul_f32_e32 v166, 0xbfb8aa3b, v145
	v_exp_f32_e32 v165, v165
	v_exp_f32_e32 v166, v166
	v_add_f32_e32 v135, 1.0, v135
	v_add_f32_e32 v160, 1.0, v160
	v_add_f32_e32 v161, 1.0, v161
	v_add_f32_e32 v162, 1.0, v162
	v_add_f32_e32 v163, 1.0, v163
	v_add_f32_e32 v164, 1.0, v164
	v_cvt_pk_f32_fp8_sdwa v[156:157], v142 src0_sel:WORD_1
	v_rcp_f32_e32 v135, v135
	v_rcp_f32_e32 v160, v160
	v_rcp_f32_e32 v161, v161
	v_rcp_f32_e32 v162, v162
	v_rcp_f32_e32 v163, v163
	v_rcp_f32_e32 v164, v164
	v_add_f32_e32 v165, 1.0, v165
	v_add_f32_e32 v166, 1.0, v166
	v_mul_f32_e32 v170, 0xbfb8aa3b, v157
	v_rcp_f32_e32 v165, v165
	v_rcp_f32_e32 v166, v166
	v_mul_f32_e32 v135, v148, v135
	v_mul_f32_e32 v148, v149, v160
	v_mul_f32_e32 v149, v150, v161
	v_mul_f32_e32 v150, v151, v162
	v_mul_f32_e32 v151, v152, v163
	v_mul_f32_e32 v152, v153, v164
	v_exp_f32_e32 v170, v170
	v_mul_f32_e32 v104, v104, v151
	v_mul_f32_e32 v105, v105, v152
	v_cvt_pk_f32_fp8_e32 v[158:159], v143
	v_cvt_scalef32_pk_fp8_f32 v147, v104, v105, s12
	v_mul_f32_e32 v144, v144, v165
	v_mul_f32_e32 v145, v145, v166
	v_add_f32_e32 v170, 1.0, v170
	v_mul_f32_e32 v106, v106, v144
	v_mul_f32_e32 v107, v107, v145
	v_rcp_f32_e32 v170, v170
	v_mul_f32_e32 v108, v108, v135
	v_mul_f32_e32 v109, v109, v148
	v_cvt_scalef32_pk_fp8_f32 v147, v106, v107, s12 op_sel:[0,0,0,1]
	v_mul_f32_e32 v107, 0xbfb8aa3b, v158
	v_cvt_scalef32_pk_fp8_f32 v146, v108, v109, s12
	v_exp_f32_e32 v107, v107
	v_mul_f32_e32 v109, 0xbfb8aa3b, v159
	v_cvt_pk_f32_fp8_e32 v[154:155], v142
	v_cvt_pk_f32_fp8_sdwa v[142:143], v143 src0_sel:WORD_1
	v_exp_f32_e32 v109, v109
	v_mul_f32_e32 v110, v110, v149
	v_mul_f32_e32 v111, v111, v150
	v_mul_f32_e32 v104, v157, v170
	v_cvt_scalef32_pk_fp8_f32 v146, v110, v111, s12 op_sel:[0,0,0,1]
	v_mul_f32_e32 v110, v127, v104
	v_add_f32_e32 v104, 1.0, v107
	v_rcp_f32_e32 v104, v104
	v_add_f32_e32 v107, 1.0, v109
	v_mul_f32_e32 v109, 0xbfb8aa3b, v142
	v_mul_f32_e32 v167, 0xbfb8aa3b, v154
	v_mul_f32_e32 v168, 0xbfb8aa3b, v155
	v_rcp_f32_e32 v107, v107
	v_exp_f32_e32 v109, v109
	v_exp_f32_e32 v167, v167
	v_exp_f32_e32 v168, v168
	v_mul_f32_e32 v104, v158, v104
	v_mul_f32_e32 v111, v120, v104
	v_mul_f32_e32 v104, v159, v107
	v_add_f32_e32 v107, 1.0, v109
	v_mul_f32_e32 v169, 0xbfb8aa3b, v156
	v_add_f32_e32 v167, 1.0, v167
	v_add_f32_e32 v168, 1.0, v168
	v_rcp_f32_e32 v107, v107
	v_mul_f32_e32 v109, 0xbfb8aa3b, v143
	v_exp_f32_e32 v169, v169
	v_rcp_f32_e32 v167, v167
	v_rcp_f32_e32 v168, v168
	v_exp_f32_e32 v109, v109
	v_mul_f32_e32 v120, v121, v104
	v_mul_f32_e32 v104, v142, v107
	v_add_f32_e32 v169, 1.0, v169
	v_mul_f32_e32 v153, v154, v167
	v_mul_f32_e32 v154, v155, v168
	v_mul_f32_e32 v107, v122, v104
	v_add_f32_e32 v104, 1.0, v109
	v_rcp_f32_e32 v169, v169
	v_mul_f32_e32 v105, v124, v153
	v_mul_f32_e32 v108, v125, v154
	v_rcp_f32_e32 v109, v104
	v_cvt_scalef32_pk_fp8_f32 v104, v105, v108, s12
	v_cvt_scalef32_pk_fp8_f32 v105, v111, v120, s12
	v_mul_f32_e32 v155, v156, v169
	v_mul_f32_e32 v108, v143, v109
	v_mul_f32_e32 v106, v126, v155
	v_mul_f32_e32 v108, v123, v108
	v_cvt_scalef32_pk_fp8_f32 v104, v106, v110, s12 op_sel:[0,0,0,1]
	v_cvt_scalef32_pk_fp8_f32 v105, v107, v108, s12 op_sel:[0,0,0,1]
	v_lshl_add_u64 v[106:107], s[38:39], 0, v[132:133]
	global_store_dwordx2 v[106:107], v[146:147], off
	global_store_dwordx2 v[106:107], v[104:105], off offset:128
	v_or_b32_e32 v104, 16, v134
	v_ashrrev_i32_e32 v105, 31, v104
	v_lshlrev_b64 v[104:105], 12, v[104:105]
	v_lshl_add_u64 v[104:105], v[104:105], 0, v[136:137]
	v_lshl_add_u64 v[106:107], s[30:31], 0, v[104:105]
	global_load_dwordx2 v[108:109], v[106:107], off
	s_nop 0
	global_load_dwordx2 v[106:107], v[106:107], off offset:128
	v_mov_b32_e32 v110, 0
	s_waitcnt vmcnt(1)
; __device__ __forceinline__ float silu_fast(float z) { return z * __builtin_amdgcn_rcpf(1.f + __builtin_amdgcn_exp2f(-1.4426950408889634f * z)); }
;   __device__ __forceinline__ void operator()(const Acc& acc, const GUnit& u, int wr, int wc, int fr, int fq) const {
;     ...
;       for (int m = 0; m < 4; ++m) {
;         const size_t off = (size_t)(row0 + ai * 128 + m * 16) * 4096 + col0;
; #pragma unroll
;         for (int bj = 0; bj < 2; ++bj) {
;           const u32x2 zw = *(const u32x2*)(Z + off + bj * 128);
;           typedef float f32x2v __attribute__((ext_vector_type(2)));
;           const f32x2v z0 = __builtin_amdgcn_cvt_pk_f32_fp8(zw[0], false), z1 = __builtin_amdgcn_cvt_pk_f32_fp8(zw[0], true), z2 = __builtin_amdgcn_cvt_pk_f32_fp8(zw[1], false), z3 = __builtin_amdgcn_cvt_pk_f32_fp8(zw[1], true);
;           f32x4 a = acc[ai][bj][m][0] * osc, b = acc[ai][bj][m][1] * osc;
;           a[0] *= silu_fast(z0[0]); a[1] *= silu_fast(z0[1]); a[2] *= silu_fast(z1[0]); a[3] *= silu_fast(z1[1]);
;           b[0] *= silu_fast(z2[0]); b[1] *= silu_fast(z2[1]); b[2] *= silu_fast(z3[0]); b[3] *= silu_fast(z3[1]);
;           u32x2 w; w[0] = __builtin_amdgcn_cvt_pk_fp8_f32(a[0], a[1], 0, false); w[0] = __builtin_amdgcn_cvt_pk_fp8_f32(a[2], a[3], w[0], true);
;           w[1] = __builtin_amdgcn_cvt_pk_fp8_f32(b[0], b[1], 0, false); w[1] = __builtin_amdgcn_cvt_pk_fp8_f32(b[2], b[3], w[1], true);
;           *(u32x2*)(Y + off + bj * 128) = w;
;         }
	v_cvt_pk_f32_fp8_e32 v[124:125], v109
	v_cvt_pk_f32_fp8_e32 v[120:121], v108
	v_cvt_pk_f32_fp8_sdwa v[122:123], v108 src0_sel:WORD_1
	v_cvt_pk_f32_fp8_sdwa v[108:109], v109 src0_sel:WORD_1
	v_mul_f32_e32 v143, 0xbfb8aa3b, v124
	v_mul_f32_e32 v144, 0xbfb8aa3b, v125
	v_exp_f32_e32 v143, v143
	v_exp_f32_e32 v144, v144
	v_mul_f32_e32 v145, 0xbfb8aa3b, v108
	v_mul_f32_e32 v146, 0xbfb8aa3b, v109
	v_exp_f32_e32 v145, v145
	v_exp_f32_e32 v146, v146
	v_add_f32_e32 v143, 1.0, v143
	v_add_f32_e32 v144, 1.0, v144
	v_rcp_f32_e32 v143, v143
	v_rcp_f32_e32 v144, v144
	v_add_f32_e32 v145, 1.0, v145
	v_add_f32_e32 v146, 1.0, v146
	v_mul_f32_e32 v126, 0xbfb8aa3b, v120
	v_rcp_f32_e32 v145, v145
	v_rcp_f32_e32 v146, v146
	v_mul_f32_e32 v124, v124, v143
	v_mul_f32_e32 v125, v125, v144
	v_exp_f32_e32 v126, v126
	v_mul_f32_e32 v88, v88, v124
	v_mul_f32_e32 v89, v89, v125
	v_cvt_scalef32_pk_fp8_f32 v111, v88, v89, s12
	v_mul_f32_e32 v108, v108, v145
	v_mul_f32_e32 v109, v109, v146
	v_add_f32_e32 v126, 1.0, v126
	v_mul_f32_e32 v88, v90, v108
	v_mul_f32_e32 v89, v91, v109
	v_rcp_f32_e32 v126, v126
	v_cvt_scalef32_pk_fp8_f32 v111, v88, v89, s12 op_sel:[0,0,0,1]
	s_waitcnt vmcnt(0)
	v_cvt_pk_f32_fp8_e32 v[88:89], v106
	v_cvt_pk_f32_fp8_sdwa v[90:91], v106 src0_sel:WORD_1
	v_mul_f32_e32 v120, v120, v126
	v_mul_f32_e32 v92, v92, v120
	v_mul_f32_e32 v106, 0xbfb8aa3b, v88
	v_exp_f32_e32 v120, v106
	v_mul_f32_e32 v127, 0xbfb8aa3b, v121
	v_mov_b32_e32 v108, v116
	v_mov_b32_e32 v109, v117
	v_exp_f32_e32 v127, v127
	v_add_f32_e32 v116, 1.0, v120
	v_rcp_f32_e32 v116, v116
	v_mul_f32_e32 v117, 0xbfb8aa3b, v89
	v_exp_f32_e32 v117, v117
	v_mul_f32_e32 v135, 0xbfb8aa3b, v122
	v_mul_f32_e32 v142, 0xbfb8aa3b, v123
	v_exp_f32_e32 v135, v135
	v_exp_f32_e32 v142, v142
	v_add_f32_e32 v127, 1.0, v127
	v_mul_f32_e32 v88, v88, v116
	v_rcp_f32_e32 v127, v127
	v_mul_f32_e32 v108, v108, v88
	v_add_f32_e32 v88, 1.0, v117
	v_mul_f32_e32 v116, 0xbfb8aa3b, v90
	v_rcp_f32_e32 v88, v88
	v_exp_f32_e32 v116, v116
	v_mul_f32_e32 v117, 0xbfb8aa3b, v91
	v_exp_f32_e32 v117, v117
	v_add_f32_e32 v135, 1.0, v135
	v_add_f32_e32 v142, 1.0, v142
	v_rcp_f32_e32 v135, v135
	v_rcp_f32_e32 v142, v142
	v_mul_f32_e32 v121, v121, v127
	v_mul_f32_e32 v93, v93, v121
	v_mul_f32_e32 v88, v89, v88
	v_add_f32_e32 v89, 1.0, v116
	v_cvt_scalef32_pk_fp8_f32 v110, v92, v93, s12
	v_cvt_pk_f32_fp8_e32 v[92:93], v107
	v_rcp_f32_e32 v89, v89
	v_add_f32_e32 v116, 1.0, v117
	v_rcp_f32_e32 v116, v116
	v_mul_f32_e32 v122, v122, v135
	v_mul_f32_e32 v123, v123, v142
	v_mul_f32_e32 v94, v94, v122
	v_mul_f32_e32 v95, v95, v123
	v_cvt_scalef32_pk_fp8_f32 v110, v94, v95, s12 op_sel:[0,0,0,1]
	v_cvt_pk_f32_fp8_sdwa v[94:95], v107 src0_sel:WORD_1
	v_mov_b32_e32 v106, v118
	v_mov_b32_e32 v107, v119
	v_mul_f32_e32 v109, v109, v88
	v_mul_f32_e32 v88, v90, v89
	v_mul_f32_e32 v89, 0xbfb8aa3b, v92
	v_mul_f32_e32 v90, v106, v88
	v_mul_f32_e32 v88, v91, v116
	v_exp_f32_e32 v89, v89
	v_mul_f32_e32 v91, 0xbfb8aa3b, v93
	v_exp_f32_e32 v91, v91
	v_mul_f32_e32 v106, v107, v88
	v_add_f32_e32 v88, 1.0, v89
	v_rcp_f32_e32 v88, v88
	v_add_f32_e32 v89, 1.0, v91
	v_mul_f32_e32 v91, 0xbfb8aa3b, v94
	v_rcp_f32_e32 v89, v89
	v_exp_f32_e32 v91, v91
	v_mul_f32_e32 v88, v92, v88
	v_mul_f32_e32 v92, v112, v88
	v_mul_f32_e32 v88, v93, v89
	v_add_f32_e32 v89, 1.0, v91
	v_rcp_f32_e32 v89, v89
	v_mul_f32_e32 v91, 0xbfb8aa3b, v95
	v_exp_f32_e32 v91, v91
	v_mul_f32_e32 v93, v113, v88
	v_mul_f32_e32 v88, v94, v89
	v_mul_f32_e32 v94, v114, v88
	v_add_f32_e32 v88, 1.0, v91
	v_rcp_f32_e32 v91, v88
	v_cvt_scalef32_pk_fp8_f32 v88, v108, v109, s12
	v_cvt_scalef32_pk_fp8_f32 v89, v92, v93, s12
	v_mul_f32_e32 v91, v95, v91
	v_mul_f32_e32 v91, v115, v91
	v_cvt_scalef32_pk_fp8_f32 v88, v90, v106, s12 op_sel:[0,0,0,1]
	v_cvt_scalef32_pk_fp8_f32 v89, v94, v91, s12 op_sel:[0,0,0,1]
	v_lshl_add_u64 v[90:91], s[38:39], 0, v[104:105]
	global_store_dwordx2 v[90:91], v[110:111], off
	global_store_dwordx2 v[90:91], v[88:89], off offset:128
	v_or_b32_e32 v88, 32, v134
	v_ashrrev_i32_e32 v89, 31, v88
	v_lshlrev_b64 v[88:89], 12, v[88:89]
	v_lshl_add_u64 v[88:89], v[88:89], 0, v[136:137]
	v_lshl_add_u64 v[90:91], s[30:31], 0, v[88:89]
	global_load_dwordx2 v[92:93], v[90:91], off
	s_nop 0
	global_load_dwordx2 v[90:91], v[90:91], off offset:128
	s_waitcnt vmcnt(1)
	v_cvt_pk_f32_fp8_e32 v[94:95], v92
	v_cvt_pk_f32_fp8_sdwa v[104:105], v92 src0_sel:WORD_1
	v_cvt_pk_f32_fp8_e32 v[106:107], v93
	v_cvt_pk_f32_fp8_sdwa v[92:93], v93 src0_sel:WORD_1
	v_mul_f32_e32 v109, 0xbfb8aa3b, v95
	v_mul_f32_e32 v108, 0xbfb8aa3b, v94
	v_exp_f32_e32 v109, v109
	v_mul_f32_e32 v110, 0xbfb8aa3b, v104
	v_exp_f32_e32 v108, v108
	v_exp_f32_e32 v110, v110
	v_mul_f32_e32 v111, 0xbfb8aa3b, v105
	v_add_f32_e32 v109, 1.0, v109
	v_exp_f32_e32 v111, v111
	v_add_f32_e32 v108, 1.0, v108
	v_rcp_f32_e32 v109, v109
	v_add_f32_e32 v110, 1.0, v110
	v_rcp_f32_e32 v108, v108
	v_rcp_f32_e32 v110, v110
	v_add_f32_e32 v111, 1.0, v111
	v_mul_f32_e32 v95, v95, v109
	v_rcp_f32_e32 v111, v111
	v_mul_f32_e32 v94, v94, v108
	v_mul_f32_e32 v77, v77, v95
	v_mul_f32_e32 v95, 0xbfb8aa3b, v106
	v_mul_f32_e32 v76, v76, v94
	v_mul_f32_e32 v94, v104, v110
	v_exp_f32_e32 v95, v95
	v_mul_f32_e32 v104, 0xbfb8aa3b, v107
	v_exp_f32_e32 v104, v104
	v_mul_f32_e32 v78, v78, v94
	v_mul_f32_e32 v94, v105, v111
	v_mul_f32_e32 v79, v79, v94
	v_add_f32_e32 v94, 1.0, v95
	v_rcp_f32_e32 v94, v94
	v_add_f32_e32 v95, 1.0, v104
	v_mul_f32_e32 v104, 0xbfb8aa3b, v92
	v_rcp_f32_e32 v95, v95
	v_exp_f32_e32 v104, v104
	v_mul_f32_e32 v94, v106, v94
	v_mul_f32_e32 v94, v72, v94
	v_mul_f32_e32 v72, v107, v95
	v_add_f32_e32 v95, 1.0, v104
	v_rcp_f32_e32 v95, v95
	v_mul_f32_e32 v104, 0xbfb8aa3b, v93
	v_exp_f32_e32 v104, v104
	v_mul_f32_e32 v105, v73, v72
	v_mul_f32_e32 v72, v92, v95
	v_mul_f32_e32 v74, v74, v72
	v_add_f32_e32 v72, 1.0, v104
	v_rcp_f32_e32 v92, v72
	v_cvt_scalef32_pk_fp8_f32 v73, v94, v105, s12
	v_cvt_scalef32_pk_fp8_f32 v72, v76, v77, s12
	v_mul_f32_e32 v76, v93, v92
	v_mul_f32_e32 v75, v75, v76
	v_cvt_scalef32_pk_fp8_f32 v73, v74, v75, s12 op_sel:[0,0,0,1]
	s_waitcnt vmcnt(0)
; __device__ __forceinline__ float silu_fast(float z) { return z * __builtin_amdgcn_rcpf(1.f + __builtin_amdgcn_exp2f(-1.4426950408889634f * z)); }
;   __device__ __forceinline__ void operator()(const Acc& acc, const GUnit& u, int wr, int wc, int fr, int fq) const {
;     ...
;       for (int m = 0; m < 4; ++m) {
;         const size_t off = (size_t)(row0 + ai * 128 + m * 16) * 4096 + col0;
; #pragma unroll
;         for (int bj = 0; bj < 2; ++bj) {
;           const u32x2 zw = *(const u32x2*)(Z + off + bj * 128);
;           typedef float f32x2v __attribute__((ext_vector_type(2)));
;           const f32x2v z0 = __builtin_amdgcn_cvt_pk_f32_fp8(zw[0], false), z1 = __builtin_amdgcn_cvt_pk_f32_fp8(zw[0], true), z2 = __builtin_amdgcn_cvt_pk_f32_fp8(zw[1], false), z3 = __builtin_amdgcn_cvt_pk_f32_fp8(zw[1], true);
;           f32x4 a = acc[ai][bj][m][0] * osc, b = acc[ai][bj][m][1] * osc;
;           a[0] *= silu_fast(z0[0]); a[1] *= silu_fast(z0[1]); a[2] *= silu_fast(z1[0]); a[3] *= silu_fast(z1[1]);
;           b[0] *= silu_fast(z2[0]); b[1] *= silu_fast(z2[1]); b[2] *= silu_fast(z3[0]); b[3] *= silu_fast(z3[1]);
;           u32x2 w; w[0] = __builtin_amdgcn_cvt_pk_fp8_f32(a[0], a[1], 0, false); w[0] = __builtin_amdgcn_cvt_pk_fp8_f32(a[2], a[3], w[0], true);
;           w[1] = __builtin_amdgcn_cvt_pk_fp8_f32(b[0], b[1], 0, false); w[1] = __builtin_amdgcn_cvt_pk_fp8_f32(b[2], b[3], w[1], true);
;           *(u32x2*)(Y + off + bj * 128) = w;
;         }
	v_cvt_pk_f32_fp8_e32 v[74:75], v90
	v_mov_b32_e32 v94, v100
	v_mov_b32_e32 v95, v101
	v_cvt_pk_f32_fp8_sdwa v[76:77], v90 src0_sel:WORD_1
	v_cvt_scalef32_pk_fp8_f32 v72, v78, v79, s12 op_sel:[0,0,0,1]
	v_mul_f32_e32 v92, 0xbfb8aa3b, v74
	v_exp_f32_e32 v104, v92
	v_mul_f32_e32 v101, 0xbfb8aa3b, v75
	v_exp_f32_e32 v101, v101
	v_cvt_pk_f32_fp8_e32 v[78:79], v91
	v_add_f32_e32 v100, 1.0, v104
	v_rcp_f32_e32 v100, v100
	v_mov_b32_e32 v92, v102
	v_mov_b32_e32 v93, v103
	v_cvt_pk_f32_fp8_sdwa v[90:91], v91 src0_sel:WORD_1
	v_mul_f32_e32 v74, v74, v100
	v_mul_f32_e32 v94, v94, v74
	v_add_f32_e32 v74, 1.0, v101
	v_mul_f32_e32 v100, 0xbfb8aa3b, v76
	v_rcp_f32_e32 v74, v74
	v_exp_f32_e32 v100, v100
	v_mul_f32_e32 v101, 0xbfb8aa3b, v77
	v_exp_f32_e32 v101, v101
	v_mul_f32_e32 v74, v75, v74
	v_add_f32_e32 v75, 1.0, v100
	v_rcp_f32_e32 v75, v75
	v_add_f32_e32 v100, 1.0, v101
	v_rcp_f32_e32 v100, v100
	v_mul_f32_e32 v95, v95, v74
	v_mul_f32_e32 v74, v76, v75
	v_mul_f32_e32 v75, 0xbfb8aa3b, v78
	v_mul_f32_e32 v76, v92, v74
	v_mul_f32_e32 v74, v77, v100
	v_exp_f32_e32 v75, v75
	v_mul_f32_e32 v77, 0xbfb8aa3b, v79
	v_exp_f32_e32 v77, v77
	v_mul_f32_e32 v92, v93, v74
	v_add_f32_e32 v74, 1.0, v75
	v_rcp_f32_e32 v74, v74
	v_add_f32_e32 v75, 1.0, v77
	v_mul_f32_e32 v77, 0xbfb8aa3b, v90
	v_rcp_f32_e32 v75, v75
	v_exp_f32_e32 v77, v77
	v_mul_f32_e32 v74, v78, v74
	v_mul_f32_e32 v78, v96, v74
	v_mul_f32_e32 v74, v79, v75
	v_add_f32_e32 v75, 1.0, v77
	v_rcp_f32_e32 v75, v75
	v_mul_f32_e32 v77, 0xbfb8aa3b, v91
	v_exp_f32_e32 v77, v77
	v_mul_f32_e32 v79, v97, v74
	v_mul_f32_e32 v74, v90, v75
	v_mul_f32_e32 v90, v98, v74
	v_add_f32_e32 v74, 1.0, v77
	v_rcp_f32_e32 v77, v74
	v_cvt_scalef32_pk_fp8_f32 v74, v94, v95, s12
	v_cvt_scalef32_pk_fp8_f32 v75, v78, v79, s12
	v_mul_f32_e32 v77, v91, v77
	v_mul_f32_e32 v77, v99, v77
	v_cvt_scalef32_pk_fp8_f32 v74, v76, v92, s12 op_sel:[0,0,0,1]
	v_cvt_scalef32_pk_fp8_f32 v75, v90, v77, s12 op_sel:[0,0,0,1]
	v_lshl_add_u64 v[76:77], s[38:39], 0, v[88:89]
	global_store_dwordx2 v[76:77], v[72:73], off
	global_store_dwordx2 v[76:77], v[74:75], off offset:128
	v_or_b32_e32 v72, 48, v134
	v_ashrrev_i32_e32 v73, 31, v72
	v_lshlrev_b64 v[72:73], 12, v[72:73]
	v_lshl_add_u64 v[72:73], v[72:73], 0, v[136:137]
	v_lshl_add_u64 v[74:75], s[30:31], 0, v[72:73]
	global_load_dwordx2 v[76:77], v[74:75], off
	s_nop 0
	global_load_dwordx2 v[74:75], v[74:75], off offset:128
	s_waitcnt vmcnt(1)
	v_cvt_pk_f32_fp8_e32 v[78:79], v76
	v_cvt_pk_f32_fp8_sdwa v[88:89], v76 src0_sel:WORD_1
	v_cvt_pk_f32_fp8_e32 v[90:91], v77
	v_cvt_pk_f32_fp8_sdwa v[76:77], v77 src0_sel:WORD_1
	v_mul_f32_e32 v92, 0xbfb8aa3b, v78
	v_exp_f32_e32 v92, v92
	v_mul_f32_e32 v93, 0xbfb8aa3b, v79
	v_exp_f32_e32 v93, v93
	v_add_f32_e32 v92, 1.0, v92
	v_rcp_f32_e32 v92, v92
	s_nop 0
	v_mul_f32_e32 v78, v78, v92
	v_mul_f32_e32 v60, v60, v78
	v_add_f32_e32 v78, 1.0, v93
	v_mul_f32_e32 v92, 0xbfb8aa3b, v88
	v_rcp_f32_e32 v78, v78
	v_exp_f32_e32 v92, v92
	v_mul_f32_e32 v93, 0xbfb8aa3b, v89
	v_exp_f32_e32 v93, v93
	v_mul_f32_e32 v78, v79, v78
	v_add_f32_e32 v79, 1.0, v92
	v_rcp_f32_e32 v79, v79
	v_add_f32_e32 v92, 1.0, v93
	v_rcp_f32_e32 v92, v92
	v_mul_f32_e32 v61, v61, v78
	v_mul_f32_e32 v78, v88, v79
	v_mul_f32_e32 v79, 0xbfb8aa3b, v90
	v_exp_f32_e32 v79, v79
	v_mul_f32_e32 v88, 0xbfb8aa3b, v91
	v_exp_f32_e32 v88, v88
	v_mul_f32_e32 v62, v62, v78
	v_mul_f32_e32 v78, v89, v92
	v_mul_f32_e32 v63, v63, v78
	v_add_f32_e32 v78, 1.0, v79
	v_rcp_f32_e32 v78, v78
	v_add_f32_e32 v79, 1.0, v88
	v_mul_f32_e32 v88, 0xbfb8aa3b, v76
	v_rcp_f32_e32 v79, v79
	v_exp_f32_e32 v88, v88
	v_mul_f32_e32 v78, v90, v78
	v_mul_f32_e32 v78, v56, v78
	v_mul_f32_e32 v56, v91, v79
	v_add_f32_e32 v79, 1.0, v88
	v_rcp_f32_e32 v79, v79
	v_mul_f32_e32 v88, 0xbfb8aa3b, v77
	v_exp_f32_e32 v88, v88
	v_mul_f32_e32 v89, v57, v56
	v_mul_f32_e32 v56, v76, v79
	v_mul_f32_e32 v58, v58, v56
	v_add_f32_e32 v56, 1.0, v88
	v_rcp_f32_e32 v76, v56
	v_cvt_scalef32_pk_fp8_f32 v57, v78, v89, s12
	v_cvt_scalef32_pk_fp8_f32 v56, v60, v61, s12
	v_mul_f32_e32 v60, v77, v76
	v_mul_f32_e32 v59, v59, v60
	v_cvt_scalef32_pk_fp8_f32 v57, v58, v59, s12 op_sel:[0,0,0,1]
	s_waitcnt vmcnt(0)
	v_cvt_pk_f32_fp8_e32 v[58:59], v74
	v_mov_b32_e32 v78, v84
	v_mov_b32_e32 v79, v85
	v_cvt_pk_f32_fp8_sdwa v[60:61], v74 src0_sel:WORD_1
	v_cvt_scalef32_pk_fp8_f32 v56, v62, v63, s12 op_sel:[0,0,0,1]
	v_mul_f32_e32 v76, 0xbfb8aa3b, v58
	v_exp_f32_e32 v88, v76
	v_mul_f32_e32 v85, 0xbfb8aa3b, v59
	v_exp_f32_e32 v85, v85
	v_cvt_pk_f32_fp8_e32 v[62:63], v75
	v_add_f32_e32 v84, 1.0, v88
	v_rcp_f32_e32 v84, v84
	v_mov_b32_e32 v76, v86
	v_mov_b32_e32 v77, v87
	v_cvt_pk_f32_fp8_sdwa v[74:75], v75 src0_sel:WORD_1
	v_mul_f32_e32 v58, v58, v84
	v_mul_f32_e32 v78, v78, v58
	v_add_f32_e32 v58, 1.0, v85
	v_mul_f32_e32 v84, 0xbfb8aa3b, v60
	v_rcp_f32_e32 v58, v58
	v_exp_f32_e32 v84, v84
	v_mul_f32_e32 v85, 0xbfb8aa3b, v61
	v_exp_f32_e32 v85, v85
	v_mul_f32_e32 v58, v59, v58
	v_add_f32_e32 v59, 1.0, v84
	v_rcp_f32_e32 v59, v59
	v_add_f32_e32 v84, 1.0, v85
	v_rcp_f32_e32 v84, v84
	v_mul_f32_e32 v79, v79, v58
	v_mul_f32_e32 v58, v60, v59
	v_mul_f32_e32 v59, 0xbfb8aa3b, v62
	v_mul_f32_e32 v60, v76, v58
	v_mul_f32_e32 v58, v61, v84
	v_exp_f32_e32 v59, v59
	v_mul_f32_e32 v61, 0xbfb8aa3b, v63
	v_exp_f32_e32 v61, v61
	v_mul_f32_e32 v76, v77, v58
	v_add_f32_e32 v58, 1.0, v59
	v_rcp_f32_e32 v58, v58
	v_add_f32_e32 v59, 1.0, v61
	v_mul_f32_e32 v61, 0xbfb8aa3b, v74
	v_rcp_f32_e32 v59, v59
	v_exp_f32_e32 v61, v61
	v_mul_f32_e32 v58, v62, v58
	v_mul_f32_e32 v62, v80, v58
	v_mul_f32_e32 v58, v63, v59
	v_add_f32_e32 v59, 1.0, v61
	v_rcp_f32_e32 v59, v59
	v_mul_f32_e32 v61, 0xbfb8aa3b, v75
	v_exp_f32_e32 v61, v61
	v_mul_f32_e32 v63, v81, v58
	v_mul_f32_e32 v58, v74, v59
	v_mul_f32_e32 v74, v82, v58
	v_add_f32_e32 v58, 1.0, v61
	v_rcp_f32_e32 v61, v58
	v_cvt_scalef32_pk_fp8_f32 v58, v78, v79, s12
	v_cvt_scalef32_pk_fp8_f32 v59, v62, v63, s12
	v_mul_f32_e32 v61, v75, v61
	v_mul_f32_e32 v61, v83, v61
	v_cvt_scalef32_pk_fp8_f32 v58, v60, v76, s12 op_sel:[0,0,0,1]
	v_cvt_scalef32_pk_fp8_f32 v59, v74, v61, s12 op_sel:[0,0,0,1]
	v_lshl_add_u64 v[60:61], s[38:39], 0, v[72:73]
	global_store_dwordx2 v[60:61], v[56:57], off
	global_store_dwordx2 v[60:61], v[58:59], off offset:128
	v_lshl_add_u64 v[56:57], v[132:133], 0, s[8:9]
	v_lshl_add_u64 v[58:59], s[30:31], 0, v[56:57]
	global_load_dwordx2 v[60:61], v[58:59], off
	s_nop 0
	global_load_dwordx2 v[58:59], v[58:59], off offset:128
	s_waitcnt vmcnt(1)
; __device__ __forceinline__ float silu_fast(float z) { return z * __builtin_amdgcn_rcpf(1.f + __builtin_amdgcn_exp2f(-1.4426950408889634f * z)); }
;   __device__ __forceinline__ void operator()(const Acc& acc, const GUnit& u, int wr, int wc, int fr, int fq) const {
;     ...
;       for (int m = 0; m < 4; ++m) {
;         const size_t off = (size_t)(row0 + ai * 128 + m * 16) * 4096 + col0;
; #pragma unroll
;         for (int bj = 0; bj < 2; ++bj) {
;           const u32x2 zw = *(const u32x2*)(Z + off + bj * 128);
;           typedef float f32x2v __attribute__((ext_vector_type(2)));
;           const f32x2v z0 = __builtin_amdgcn_cvt_pk_f32_fp8(zw[0], false), z1 = __builtin_amdgcn_cvt_pk_f32_fp8(zw[0], true), z2 = __builtin_amdgcn_cvt_pk_f32_fp8(zw[1], false), z3 = __builtin_amdgcn_cvt_pk_f32_fp8(zw[1], true);
;           f32x4 a = acc[ai][bj][m][0] * osc, b = acc[ai][bj][m][1] * osc;
;           a[0] *= silu_fast(z0[0]); a[1] *= silu_fast(z0[1]); a[2] *= silu_fast(z1[0]); a[3] *= silu_fast(z1[1]);
;           b[0] *= silu_fast(z2[0]); b[1] *= silu_fast(z2[1]); b[2] *= silu_fast(z3[0]); b[3] *= silu_fast(z3[1]);
;           u32x2 w; w[0] = __builtin_amdgcn_cvt_pk_fp8_f32(a[0], a[1], 0, false); w[0] = __builtin_amdgcn_cvt_pk_fp8_f32(a[2], a[3], w[0], true);
;           w[1] = __builtin_amdgcn_cvt_pk_fp8_f32(b[0], b[1], 0, false); w[1] = __builtin_amdgcn_cvt_pk_fp8_f32(b[2], b[3], w[1], true);
;           *(u32x2*)(Y + off + bj * 128) = w;
;         }
	v_cvt_pk_f32_fp8_e32 v[62:63], v60
	v_cvt_pk_f32_fp8_sdwa v[72:73], v60 src0_sel:WORD_1
	v_cvt_pk_f32_fp8_e32 v[74:75], v61
	v_cvt_pk_f32_fp8_sdwa v[60:61], v61 src0_sel:WORD_1
	v_mul_f32_e32 v76, 0xbfb8aa3b, v62
	v_exp_f32_e32 v76, v76
	v_mul_f32_e32 v77, 0xbfb8aa3b, v63
	v_exp_f32_e32 v77, v77
	v_add_f32_e32 v76, 1.0, v76
	v_rcp_f32_e32 v76, v76
	s_nop 0
	v_mul_f32_e32 v62, v62, v76
	v_mul_f32_e32 v44, v44, v62
	v_add_f32_e32 v62, 1.0, v77
	v_mul_f32_e32 v76, 0xbfb8aa3b, v72
	v_rcp_f32_e32 v62, v62
	v_exp_f32_e32 v76, v76
	v_mul_f32_e32 v77, 0xbfb8aa3b, v73
	v_exp_f32_e32 v77, v77
	v_mul_f32_e32 v62, v63, v62
	v_add_f32_e32 v63, 1.0, v76
	v_rcp_f32_e32 v63, v63
	v_add_f32_e32 v76, 1.0, v77
	v_rcp_f32_e32 v76, v76
	v_mul_f32_e32 v45, v45, v62
	v_mul_f32_e32 v62, v72, v63
	v_mul_f32_e32 v63, 0xbfb8aa3b, v74
	v_exp_f32_e32 v63, v63
	v_mul_f32_e32 v72, 0xbfb8aa3b, v75
	v_exp_f32_e32 v72, v72
	v_mul_f32_e32 v46, v46, v62
	v_mul_f32_e32 v62, v73, v76
	v_mul_f32_e32 v47, v47, v62
	v_add_f32_e32 v62, 1.0, v63
	v_rcp_f32_e32 v62, v62
	v_add_f32_e32 v63, 1.0, v72
	v_mul_f32_e32 v72, 0xbfb8aa3b, v60
	v_rcp_f32_e32 v63, v63
	v_exp_f32_e32 v72, v72
	v_mul_f32_e32 v62, v74, v62
	v_mul_f32_e32 v62, v40, v62
	v_mul_f32_e32 v40, v75, v63
	v_add_f32_e32 v63, 1.0, v72
	v_rcp_f32_e32 v63, v63
	v_mul_f32_e32 v72, 0xbfb8aa3b, v61
	v_exp_f32_e32 v72, v72
	v_mul_f32_e32 v73, v41, v40
	v_mul_f32_e32 v40, v60, v63
	v_mul_f32_e32 v42, v42, v40
	v_add_f32_e32 v40, 1.0, v72
	v_rcp_f32_e32 v60, v40
	v_cvt_scalef32_pk_fp8_f32 v41, v62, v73, s12
	v_cvt_scalef32_pk_fp8_f32 v40, v44, v45, s12
	v_mul_f32_e32 v44, v61, v60
	v_mul_f32_e32 v43, v43, v44
	v_cvt_scalef32_pk_fp8_f32 v41, v42, v43, s12 op_sel:[0,0,0,1]
	s_waitcnt vmcnt(0)
	v_cvt_pk_f32_fp8_e32 v[42:43], v58
	v_mov_b32_e32 v62, v68
	v_mov_b32_e32 v63, v69
	v_cvt_pk_f32_fp8_sdwa v[44:45], v58 src0_sel:WORD_1
	v_cvt_scalef32_pk_fp8_f32 v40, v46, v47, s12 op_sel:[0,0,0,1]
	v_mul_f32_e32 v60, 0xbfb8aa3b, v42
	v_exp_f32_e32 v72, v60
	v_mul_f32_e32 v69, 0xbfb8aa3b, v43
	v_exp_f32_e32 v69, v69
	v_cvt_pk_f32_fp8_e32 v[46:47], v59
	v_add_f32_e32 v68, 1.0, v72
	v_rcp_f32_e32 v68, v68
	v_mov_b32_e32 v60, v70
	v_mov_b32_e32 v61, v71
	v_cvt_pk_f32_fp8_sdwa v[58:59], v59 src0_sel:WORD_1
	v_mul_f32_e32 v42, v42, v68
	v_mul_f32_e32 v62, v62, v42
	v_add_f32_e32 v42, 1.0, v69
	v_mul_f32_e32 v68, 0xbfb8aa3b, v44
	v_rcp_f32_e32 v42, v42
	v_exp_f32_e32 v68, v68
	v_mul_f32_e32 v69, 0xbfb8aa3b, v45
	v_exp_f32_e32 v69, v69
	v_mul_f32_e32 v42, v43, v42
	v_add_f32_e32 v43, 1.0, v68
	v_rcp_f32_e32 v43, v43
	v_add_f32_e32 v68, 1.0, v69
	v_rcp_f32_e32 v68, v68
	v_mul_f32_e32 v63, v63, v42
	v_mul_f32_e32 v42, v44, v43
	v_mul_f32_e32 v43, 0xbfb8aa3b, v46
	v_mul_f32_e32 v44, v60, v42
	v_mul_f32_e32 v42, v45, v68
	v_exp_f32_e32 v43, v43
	v_mul_f32_e32 v45, 0xbfb8aa3b, v47
	v_exp_f32_e32 v45, v45
	v_mul_f32_e32 v60, v61, v42
	v_add_f32_e32 v42, 1.0, v43
	v_rcp_f32_e32 v42, v42
	v_add_f32_e32 v43, 1.0, v45
	v_mul_f32_e32 v45, 0xbfb8aa3b, v58
	v_rcp_f32_e32 v43, v43
	v_exp_f32_e32 v45, v45
	v_mul_f32_e32 v42, v46, v42
	v_mul_f32_e32 v46, v64, v42
	v_mul_f32_e32 v42, v47, v43
	v_add_f32_e32 v43, 1.0, v45
	v_rcp_f32_e32 v43, v43
	v_mul_f32_e32 v45, 0xbfb8aa3b, v59
	v_exp_f32_e32 v45, v45
	v_mul_f32_e32 v47, v65, v42
	v_mul_f32_e32 v42, v58, v43
	v_mul_f32_e32 v58, v66, v42
	v_add_f32_e32 v42, 1.0, v45
	v_rcp_f32_e32 v45, v42
	v_cvt_scalef32_pk_fp8_f32 v42, v62, v63, s12
	v_cvt_scalef32_pk_fp8_f32 v43, v46, v47, s12
	v_mul_f32_e32 v45, v59, v45
	v_mul_f32_e32 v45, v67, v45
	v_cvt_scalef32_pk_fp8_f32 v42, v44, v60, s12 op_sel:[0,0,0,1]
	v_cvt_scalef32_pk_fp8_f32 v43, v58, v45, s12 op_sel:[0,0,0,1]
	v_lshl_add_u64 v[44:45], s[38:39], 0, v[56:57]
	global_store_dwordx2 v[44:45], v[40:41], off
	global_store_dwordx2 v[44:45], v[42:43], off offset:128
	v_lshl_add_u64 v[40:41], v[132:133], 0, s[14:15]
	v_lshl_add_u64 v[42:43], s[30:31], 0, v[40:41]
	global_load_dwordx2 v[44:45], v[42:43], off
	s_nop 0
	global_load_dwordx2 v[42:43], v[42:43], off offset:128
	s_waitcnt vmcnt(1)
	v_cvt_pk_f32_fp8_e32 v[46:47], v44
	v_cvt_pk_f32_fp8_sdwa v[56:57], v44 src0_sel:WORD_1
	v_cvt_pk_f32_fp8_e32 v[58:59], v45
	v_cvt_pk_f32_fp8_sdwa v[44:45], v45 src0_sel:WORD_1
	v_mul_f32_e32 v60, 0xbfb8aa3b, v46
	v_exp_f32_e32 v60, v60
	v_mul_f32_e32 v61, 0xbfb8aa3b, v47
	v_exp_f32_e32 v61, v61
	v_add_f32_e32 v60, 1.0, v60
	v_rcp_f32_e32 v60, v60
	s_nop 0
	v_mul_f32_e32 v46, v46, v60
	v_mul_f32_e32 v28, v28, v46
	v_add_f32_e32 v46, 1.0, v61
	v_mul_f32_e32 v60, 0xbfb8aa3b, v56
	v_rcp_f32_e32 v46, v46
	v_exp_f32_e32 v60, v60
	v_mul_f32_e32 v61, 0xbfb8aa3b, v57
	v_exp_f32_e32 v61, v61
	v_mul_f32_e32 v46, v47, v46
	v_add_f32_e32 v47, 1.0, v60
	v_rcp_f32_e32 v47, v47
	v_add_f32_e32 v60, 1.0, v61
	v_rcp_f32_e32 v60, v60
	v_mul_f32_e32 v29, v29, v46
	v_mul_f32_e32 v46, v56, v47
	v_mul_f32_e32 v47, 0xbfb8aa3b, v58
	v_exp_f32_e32 v47, v47
	v_mul_f32_e32 v56, 0xbfb8aa3b, v59
	v_exp_f32_e32 v56, v56
	v_mul_f32_e32 v30, v30, v46
	v_mul_f32_e32 v46, v57, v60
	v_mul_f32_e32 v31, v31, v46
	v_add_f32_e32 v46, 1.0, v47
	v_rcp_f32_e32 v46, v46
	v_add_f32_e32 v47, 1.0, v56
	v_mul_f32_e32 v56, 0xbfb8aa3b, v44
	v_rcp_f32_e32 v47, v47
	v_exp_f32_e32 v56, v56
	v_mul_f32_e32 v46, v58, v46
	v_mul_f32_e32 v46, v24, v46
	v_mul_f32_e32 v24, v59, v47
	v_add_f32_e32 v47, 1.0, v56
	v_rcp_f32_e32 v47, v47
	v_mul_f32_e32 v56, 0xbfb8aa3b, v45
	v_exp_f32_e32 v56, v56
	v_mul_f32_e32 v57, v25, v24
	v_mul_f32_e32 v24, v44, v47
	v_mul_f32_e32 v26, v26, v24
	v_add_f32_e32 v24, 1.0, v56
	v_rcp_f32_e32 v44, v24
	v_cvt_scalef32_pk_fp8_f32 v25, v46, v57, s12
	v_cvt_scalef32_pk_fp8_f32 v24, v28, v29, s12
	v_mul_f32_e32 v28, v45, v44
	v_mul_f32_e32 v27, v27, v28
	v_cvt_scalef32_pk_fp8_f32 v25, v26, v27, s12 op_sel:[0,0,0,1]
	s_waitcnt vmcnt(0)
; __device__ __forceinline__ float silu_fast(float z) { return z * __builtin_amdgcn_rcpf(1.f + __builtin_amdgcn_exp2f(-1.4426950408889634f * z)); }
;   __device__ __forceinline__ void operator()(const Acc& acc, const GUnit& u, int wr, int wc, int fr, int fq) const {
;     ...
;       for (int m = 0; m < 4; ++m) {
;         const size_t off = (size_t)(row0 + ai * 128 + m * 16) * 4096 + col0;
; #pragma unroll
;         for (int bj = 0; bj < 2; ++bj) {
;           const u32x2 zw = *(const u32x2*)(Z + off + bj * 128);
;           typedef float f32x2v __attribute__((ext_vector_type(2)));
;           const f32x2v z0 = __builtin_amdgcn_cvt_pk_f32_fp8(zw[0], false), z1 = __builtin_amdgcn_cvt_pk_f32_fp8(zw[0], true), z2 = __builtin_amdgcn_cvt_pk_f32_fp8(zw[1], false), z3 = __builtin_amdgcn_cvt_pk_f32_fp8(zw[1], true);
;           f32x4 a = acc[ai][bj][m][0] * osc, b = acc[ai][bj][m][1] * osc;
;           a[0] *= silu_fast(z0[0]); a[1] *= silu_fast(z0[1]); a[2] *= silu_fast(z1[0]); a[3] *= silu_fast(z1[1]);
;           b[0] *= silu_fast(z2[0]); b[1] *= silu_fast(z2[1]); b[2] *= silu_fast(z3[0]); b[3] *= silu_fast(z3[1]);
;           u32x2 w; w[0] = __builtin_amdgcn_cvt_pk_fp8_f32(a[0], a[1], 0, false); w[0] = __builtin_amdgcn_cvt_pk_fp8_f32(a[2], a[3], w[0], true);
;           w[1] = __builtin_amdgcn_cvt_pk_fp8_f32(b[0], b[1], 0, false); w[1] = __builtin_amdgcn_cvt_pk_fp8_f32(b[2], b[3], w[1], true);
;           *(u32x2*)(Y + off + bj * 128) = w;
;         }
	v_cvt_pk_f32_fp8_e32 v[26:27], v42
	v_mov_b32_e32 v46, v52
	v_mov_b32_e32 v47, v53
	v_cvt_pk_f32_fp8_sdwa v[28:29], v42 src0_sel:WORD_1
	v_cvt_scalef32_pk_fp8_f32 v24, v30, v31, s12 op_sel:[0,0,0,1]
	v_mul_f32_e32 v44, 0xbfb8aa3b, v26
	v_exp_f32_e32 v56, v44
	v_mul_f32_e32 v53, 0xbfb8aa3b, v27
	v_exp_f32_e32 v53, v53
	v_cvt_pk_f32_fp8_e32 v[30:31], v43
	v_add_f32_e32 v52, 1.0, v56
	v_rcp_f32_e32 v52, v52
	v_mov_b32_e32 v44, v54
	v_mov_b32_e32 v45, v55
	v_cvt_pk_f32_fp8_sdwa v[42:43], v43 src0_sel:WORD_1
	v_mul_f32_e32 v26, v26, v52
	v_mul_f32_e32 v46, v46, v26
	v_add_f32_e32 v26, 1.0, v53
	v_mul_f32_e32 v52, 0xbfb8aa3b, v28
	v_rcp_f32_e32 v26, v26
	v_exp_f32_e32 v52, v52
	v_mul_f32_e32 v53, 0xbfb8aa3b, v29
	v_exp_f32_e32 v53, v53
	v_mul_f32_e32 v26, v27, v26
	v_add_f32_e32 v27, 1.0, v52
	v_rcp_f32_e32 v27, v27
	v_add_f32_e32 v52, 1.0, v53
	v_rcp_f32_e32 v52, v52
	v_mul_f32_e32 v47, v47, v26
	v_mul_f32_e32 v26, v28, v27
	v_mul_f32_e32 v27, 0xbfb8aa3b, v30
	v_mul_f32_e32 v28, v44, v26
	v_mul_f32_e32 v26, v29, v52
	v_exp_f32_e32 v27, v27
	v_mul_f32_e32 v29, 0xbfb8aa3b, v31
	v_exp_f32_e32 v29, v29
	v_mul_f32_e32 v44, v45, v26
	v_add_f32_e32 v26, 1.0, v27
	v_rcp_f32_e32 v26, v26
	v_add_f32_e32 v27, 1.0, v29
	v_mul_f32_e32 v29, 0xbfb8aa3b, v42
	v_rcp_f32_e32 v27, v27
	v_exp_f32_e32 v29, v29
	v_mul_f32_e32 v26, v30, v26
	v_mul_f32_e32 v30, v48, v26
	v_mul_f32_e32 v26, v31, v27
	v_add_f32_e32 v27, 1.0, v29
	v_rcp_f32_e32 v27, v27
	v_mul_f32_e32 v29, 0xbfb8aa3b, v43
	v_exp_f32_e32 v29, v29
	v_mul_f32_e32 v31, v49, v26
	v_mul_f32_e32 v26, v42, v27
	v_mul_f32_e32 v42, v50, v26
	v_add_f32_e32 v26, 1.0, v29
	v_rcp_f32_e32 v29, v26
	v_cvt_scalef32_pk_fp8_f32 v26, v46, v47, s12
	v_cvt_scalef32_pk_fp8_f32 v27, v30, v31, s12
	v_mul_f32_e32 v29, v43, v29
	v_mul_f32_e32 v29, v51, v29
	v_cvt_scalef32_pk_fp8_f32 v26, v28, v44, s12 op_sel:[0,0,0,1]
	v_cvt_scalef32_pk_fp8_f32 v27, v42, v29, s12 op_sel:[0,0,0,1]
	v_lshl_add_u64 v[28:29], s[38:39], 0, v[40:41]
	global_store_dwordx2 v[28:29], v[24:25], off
	global_store_dwordx2 v[28:29], v[26:27], off offset:128
	v_lshl_add_u64 v[24:25], v[132:133], 0, s[16:17]
	v_lshl_add_u64 v[26:27], s[30:31], 0, v[24:25]
	global_load_dwordx2 v[28:29], v[26:27], off
	s_nop 0
	global_load_dwordx2 v[26:27], v[26:27], off offset:128
	s_waitcnt vmcnt(1)
	v_cvt_pk_f32_fp8_e32 v[30:31], v28
	v_cvt_pk_f32_fp8_sdwa v[40:41], v28 src0_sel:WORD_1
	v_cvt_pk_f32_fp8_e32 v[42:43], v29
	v_cvt_pk_f32_fp8_sdwa v[28:29], v29 src0_sel:WORD_1
	v_mul_f32_e32 v44, 0xbfb8aa3b, v30
	v_exp_f32_e32 v44, v44
	v_mul_f32_e32 v45, 0xbfb8aa3b, v31
	v_exp_f32_e32 v45, v45
	v_add_f32_e32 v44, 1.0, v44
	v_rcp_f32_e32 v44, v44
	s_nop 0
	v_mul_f32_e32 v30, v30, v44
	v_mul_f32_e32 v12, v12, v30
	v_add_f32_e32 v30, 1.0, v45
	v_mul_f32_e32 v44, 0xbfb8aa3b, v40
	v_rcp_f32_e32 v30, v30
	v_exp_f32_e32 v44, v44
	v_mul_f32_e32 v45, 0xbfb8aa3b, v41
	v_exp_f32_e32 v45, v45
	v_mul_f32_e32 v30, v31, v30
	v_add_f32_e32 v31, 1.0, v44
	v_rcp_f32_e32 v31, v31
	v_add_f32_e32 v44, 1.0, v45
	v_rcp_f32_e32 v44, v44
	v_mul_f32_e32 v13, v13, v30
	v_mul_f32_e32 v30, v40, v31
	v_mul_f32_e32 v31, 0xbfb8aa3b, v42
	v_exp_f32_e32 v31, v31
	v_mul_f32_e32 v40, 0xbfb8aa3b, v43
	v_exp_f32_e32 v40, v40
	v_mul_f32_e32 v14, v14, v30
	v_mul_f32_e32 v30, v41, v44
	v_mul_f32_e32 v15, v15, v30
	v_add_f32_e32 v30, 1.0, v31
	v_rcp_f32_e32 v30, v30
	v_add_f32_e32 v31, 1.0, v40
	v_mul_f32_e32 v40, 0xbfb8aa3b, v28
	v_rcp_f32_e32 v31, v31
	v_exp_f32_e32 v40, v40
	v_mul_f32_e32 v30, v42, v30
	v_mul_f32_e32 v30, v8, v30
	v_mul_f32_e32 v8, v43, v31
	v_add_f32_e32 v31, 1.0, v40
	v_rcp_f32_e32 v31, v31
	v_mul_f32_e32 v40, 0xbfb8aa3b, v29
	v_exp_f32_e32 v40, v40
	v_mul_f32_e32 v41, v9, v8
	v_mul_f32_e32 v8, v28, v31
	v_mul_f32_e32 v10, v10, v8
	v_add_f32_e32 v8, 1.0, v40
	v_rcp_f32_e32 v28, v8
	v_cvt_scalef32_pk_fp8_f32 v9, v30, v41, s12
	v_cvt_scalef32_pk_fp8_f32 v8, v12, v13, s12
	v_mul_f32_e32 v12, v29, v28
	v_mul_f32_e32 v11, v11, v12
	v_cvt_scalef32_pk_fp8_f32 v9, v10, v11, s12 op_sel:[0,0,0,1]
	s_waitcnt vmcnt(0)
; __device__ __forceinline__ float silu_fast(float z) { return z * __builtin_amdgcn_rcpf(1.f + __builtin_amdgcn_exp2f(-1.4426950408889634f * z)); }
;   __device__ __forceinline__ void operator()(const Acc& acc, const GUnit& u, int wr, int wc, int fr, int fq) const {
;     ...
;       for (int m = 0; m < 4; ++m) {
;         const size_t off = (size_t)(row0 + ai * 128 + m * 16) * 4096 + col0;
; #pragma unroll
;         for (int bj = 0; bj < 2; ++bj) {
;           const u32x2 zw = *(const u32x2*)(Z + off + bj * 128);
;           typedef float f32x2v __attribute__((ext_vector_type(2)));
;           const f32x2v z0 = __builtin_amdgcn_cvt_pk_f32_fp8(zw[0], false), z1 = __builtin_amdgcn_cvt_pk_f32_fp8(zw[0], true), z2 = __builtin_amdgcn_cvt_pk_f32_fp8(zw[1], false), z3 = __builtin_amdgcn_cvt_pk_f32_fp8(zw[1], true);
;           f32x4 a = acc[ai][bj][m][0] * osc, b = acc[ai][bj][m][1] * osc;
;           a[0] *= silu_fast(z0[0]); a[1] *= silu_fast(z0[1]); a[2] *= silu_fast(z1[0]); a[3] *= silu_fast(z1[1]);
;           b[0] *= silu_fast(z2[0]); b[1] *= silu_fast(z2[1]); b[2] *= silu_fast(z3[0]); b[3] *= silu_fast(z3[1]);
;           u32x2 w; w[0] = __builtin_amdgcn_cvt_pk_fp8_f32(a[0], a[1], 0, false); w[0] = __builtin_amdgcn_cvt_pk_fp8_f32(a[2], a[3], w[0], true);
;           w[1] = __builtin_amdgcn_cvt_pk_fp8_f32(b[0], b[1], 0, false); w[1] = __builtin_amdgcn_cvt_pk_fp8_f32(b[2], b[3], w[1], true);
;           *(u32x2*)(Y + off + bj * 128) = w;
;         }
	v_cvt_pk_f32_fp8_e32 v[10:11], v26
	v_mov_b32_e32 v30, v36
	v_mov_b32_e32 v31, v37
	v_cvt_pk_f32_fp8_sdwa v[12:13], v26 src0_sel:WORD_1
	v_cvt_scalef32_pk_fp8_f32 v8, v14, v15, s12 op_sel:[0,0,0,1]
	v_mul_f32_e32 v28, 0xbfb8aa3b, v10
	v_exp_f32_e32 v40, v28
	v_mul_f32_e32 v37, 0xbfb8aa3b, v11
	v_exp_f32_e32 v37, v37
	v_cvt_pk_f32_fp8_e32 v[14:15], v27
	v_add_f32_e32 v36, 1.0, v40
	v_rcp_f32_e32 v36, v36
	v_mov_b32_e32 v28, v38
	v_mov_b32_e32 v29, v39
	v_cvt_pk_f32_fp8_sdwa v[26:27], v27 src0_sel:WORD_1
	v_mul_f32_e32 v10, v10, v36
	v_mul_f32_e32 v30, v30, v10
	v_add_f32_e32 v10, 1.0, v37
	v_mul_f32_e32 v36, 0xbfb8aa3b, v12
	v_rcp_f32_e32 v10, v10
	v_exp_f32_e32 v36, v36
	v_mul_f32_e32 v37, 0xbfb8aa3b, v13
	v_exp_f32_e32 v37, v37
	v_mul_f32_e32 v10, v11, v10
	v_add_f32_e32 v11, 1.0, v36
	v_rcp_f32_e32 v11, v11
	v_add_f32_e32 v36, 1.0, v37
	v_rcp_f32_e32 v36, v36
	v_mul_f32_e32 v31, v31, v10
	v_mul_f32_e32 v10, v12, v11
	v_mul_f32_e32 v11, 0xbfb8aa3b, v14
	v_mul_f32_e32 v12, v28, v10
	v_mul_f32_e32 v10, v13, v36
	v_exp_f32_e32 v11, v11
	v_mul_f32_e32 v13, 0xbfb8aa3b, v15
	v_exp_f32_e32 v13, v13
	v_mul_f32_e32 v28, v29, v10
	v_add_f32_e32 v10, 1.0, v11
	v_rcp_f32_e32 v10, v10
	v_add_f32_e32 v11, 1.0, v13
	v_mul_f32_e32 v13, 0xbfb8aa3b, v26
	v_rcp_f32_e32 v11, v11
	v_exp_f32_e32 v13, v13
	v_mul_f32_e32 v10, v14, v10
	v_mul_f32_e32 v14, v32, v10
	v_mul_f32_e32 v10, v15, v11
	v_add_f32_e32 v11, 1.0, v13
	v_rcp_f32_e32 v11, v11
	v_mul_f32_e32 v13, 0xbfb8aa3b, v27
	v_exp_f32_e32 v13, v13
	v_mul_f32_e32 v15, v33, v10
	v_mul_f32_e32 v10, v26, v11
	v_mul_f32_e32 v26, v34, v10
	v_add_f32_e32 v10, 1.0, v13
	v_rcp_f32_e32 v13, v10
	v_cvt_scalef32_pk_fp8_f32 v10, v30, v31, s12
	v_cvt_scalef32_pk_fp8_f32 v11, v14, v15, s12
	v_mul_f32_e32 v13, v27, v13
	v_mul_f32_e32 v13, v35, v13
	v_cvt_scalef32_pk_fp8_f32 v10, v12, v28, s12 op_sel:[0,0,0,1]
	v_cvt_scalef32_pk_fp8_f32 v11, v26, v13, s12 op_sel:[0,0,0,1]
	v_lshl_add_u64 v[12:13], s[38:39], 0, v[24:25]
	global_store_dwordx2 v[12:13], v[8:9], off
	global_store_dwordx2 v[12:13], v[10:11], off offset:128
	v_lshl_add_u64 v[8:9], v[132:133], 0, s[18:19]
	v_lshl_add_u64 v[10:11], s[30:31], 0, v[8:9]
	global_load_dwordx2 v[12:13], v[10:11], off
	s_nop 0
	global_load_dwordx2 v[10:11], v[10:11], off offset:128
	s_waitcnt vmcnt(1)
	v_cvt_pk_f32_fp8_e32 v[14:15], v12
	v_cvt_pk_f32_fp8_sdwa v[24:25], v12 src0_sel:WORD_1
	v_cvt_pk_f32_fp8_e32 v[26:27], v13
	v_cvt_pk_f32_fp8_sdwa v[12:13], v13 src0_sel:WORD_1
	v_mul_f32_e32 v28, 0xbfb8aa3b, v14
	v_exp_f32_e32 v28, v28
	v_mul_f32_e32 v29, 0xbfb8aa3b, v15
	v_exp_f32_e32 v29, v29
	v_add_f32_e32 v28, 1.0, v28
	v_rcp_f32_e32 v28, v28
	s_nop 0
	v_mul_f32_e32 v14, v14, v28
	v_mul_f32_e32 v4, v4, v14
	v_add_f32_e32 v14, 1.0, v29
	v_mul_f32_e32 v28, 0xbfb8aa3b, v24
	v_rcp_f32_e32 v14, v14
	v_exp_f32_e32 v28, v28
	v_mul_f32_e32 v29, 0xbfb8aa3b, v25
	v_exp_f32_e32 v29, v29
	v_mul_f32_e32 v14, v15, v14
	v_add_f32_e32 v15, 1.0, v28
	v_rcp_f32_e32 v15, v15
	v_add_f32_e32 v28, 1.0, v29
	v_rcp_f32_e32 v28, v28
	v_mul_f32_e32 v5, v5, v14
	v_mul_f32_e32 v14, v24, v15
	v_mul_f32_e32 v15, 0xbfb8aa3b, v26
	v_exp_f32_e32 v15, v15
	v_mul_f32_e32 v24, 0xbfb8aa3b, v27
	v_exp_f32_e32 v24, v24
	v_mul_f32_e32 v6, v6, v14
	v_mul_f32_e32 v14, v25, v28
	v_mul_f32_e32 v7, v7, v14
	v_add_f32_e32 v14, 1.0, v15
	v_rcp_f32_e32 v14, v14
	v_add_f32_e32 v15, 1.0, v24
	v_mul_f32_e32 v24, 0xbfb8aa3b, v12
	v_rcp_f32_e32 v15, v15
	v_exp_f32_e32 v24, v24
	v_mul_f32_e32 v14, v26, v14
	v_mul_f32_e32 v14, v0, v14
	v_mul_f32_e32 v0, v27, v15
	v_add_f32_e32 v15, 1.0, v24
	v_rcp_f32_e32 v15, v15
	v_mul_f32_e32 v24, 0xbfb8aa3b, v13
	v_exp_f32_e32 v24, v24
	v_mul_f32_e32 v25, v1, v0
	v_mul_f32_e32 v0, v12, v15
	v_mul_f32_e32 v2, v2, v0
	v_add_f32_e32 v0, 1.0, v24
	v_rcp_f32_e32 v12, v0
	v_cvt_scalef32_pk_fp8_f32 v1, v14, v25, s12
	v_cvt_scalef32_pk_fp8_f32 v0, v4, v5, s12
	v_mul_f32_e32 v4, v13, v12
	v_mul_f32_e32 v3, v3, v4
	v_cvt_scalef32_pk_fp8_f32 v1, v2, v3, s12 op_sel:[0,0,0,1]
	s_waitcnt vmcnt(0)
	v_cvt_pk_f32_fp8_e32 v[2:3], v10
	v_mov_b32_e32 v14, v20
	v_mov_b32_e32 v15, v21
	v_cvt_pk_f32_fp8_sdwa v[4:5], v10 src0_sel:WORD_1
	v_cvt_scalef32_pk_fp8_f32 v0, v6, v7, s12 op_sel:[0,0,0,1]
	v_mul_f32_e32 v12, 0xbfb8aa3b, v2
	v_exp_f32_e32 v24, v12
	v_mul_f32_e32 v21, 0xbfb8aa3b, v3
	v_exp_f32_e32 v21, v21
	v_cvt_pk_f32_fp8_e32 v[6:7], v11
	v_add_f32_e32 v20, 1.0, v24
	v_rcp_f32_e32 v20, v20
	v_mov_b32_e32 v12, v22
	v_mov_b32_e32 v13, v23
	v_cvt_pk_f32_fp8_sdwa v[10:11], v11 src0_sel:WORD_1
	v_mul_f32_e32 v2, v2, v20
	v_mul_f32_e32 v14, v14, v2
	v_add_f32_e32 v2, 1.0, v21
	v_mul_f32_e32 v20, 0xbfb8aa3b, v4
	v_rcp_f32_e32 v2, v2
	v_exp_f32_e32 v20, v20
	v_mul_f32_e32 v21, 0xbfb8aa3b, v5
	v_exp_f32_e32 v21, v21
	v_mul_f32_e32 v2, v3, v2
	v_add_f32_e32 v3, 1.0, v20
	v_rcp_f32_e32 v3, v3
	v_add_f32_e32 v20, 1.0, v21
	v_rcp_f32_e32 v20, v20
	v_mul_f32_e32 v15, v15, v2
	v_mul_f32_e32 v2, v4, v3
	v_mul_f32_e32 v3, 0xbfb8aa3b, v6
	v_mul_f32_e32 v4, v12, v2
	v_mul_f32_e32 v2, v5, v20
	v_exp_f32_e32 v3, v3
	v_mul_f32_e32 v5, 0xbfb8aa3b, v7
	v_exp_f32_e32 v5, v5
	v_mul_f32_e32 v12, v13, v2
	v_add_f32_e32 v2, 1.0, v3
	v_rcp_f32_e32 v2, v2
	v_add_f32_e32 v3, 1.0, v5
	v_mul_f32_e32 v5, 0xbfb8aa3b, v10
	v_rcp_f32_e32 v3, v3
	v_exp_f32_e32 v5, v5
	v_mul_f32_e32 v2, v6, v2
	v_mul_f32_e32 v6, v16, v2
	v_mul_f32_e32 v2, v7, v3
	v_add_f32_e32 v3, 1.0, v5
	v_rcp_f32_e32 v3, v3
	v_mul_f32_e32 v5, 0xbfb8aa3b, v11
	v_exp_f32_e32 v5, v5
	v_mul_f32_e32 v7, v17, v2
	v_mul_f32_e32 v2, v10, v3
	v_mul_f32_e32 v10, v18, v2
	v_add_f32_e32 v2, 1.0, v5
	v_rcp_f32_e32 v5, v2
	v_cvt_scalef32_pk_fp8_f32 v2, v14, v15, s12
	v_cvt_scalef32_pk_fp8_f32 v3, v6, v7, s12
	v_mul_f32_e32 v5, v11, v5
	v_mul_f32_e32 v5, v19, v5
	v_cvt_scalef32_pk_fp8_f32 v2, v4, v12, s12 op_sel:[0,0,0,1]
	v_cvt_scalef32_pk_fp8_f32 v3, v10, v5, s12 op_sel:[0,0,0,1]
	v_lshl_add_u64 v[4:5], s[38:39], 0, v[8:9]
	global_store_dwordx2 v[4:5], v[0:1], off
	global_store_dwordx2 v[4:5], v[2:3], off offset:128
	s_cbranch_vccnz .LBB0_1037
	s_andn2_b64 vcc, exec, s[4:5]
	s_cbranch_vccnz .LBB0_1036
	s_barrier
	s_branch .LBB0_1036
